# P9 GLA scan: counted vmcnt waits instead of full drains at loop heads (prefetch stays in flight)
# speedup vs baseline: 1.0485x; 1.0485x over previous
; #define LAS __attribute__((address_space(3)))
; template <bool RO>
; __device__ __forceinline__ void p9_job(LAS unsigned char* lds, const bf16_t* __restrict__ kap, const bf16_t* __restrict__ vbp, const float* __restrict__ dcp, const bf16_t* __restrict__ qap, bf16_t* __restrict__ op, int wave, int c16, int kq) {
;     constexpr int PD = P9_DEPTH, NCT = P9_NCT;
;     f32x4 S[NCT];
; #pragma unroll
;     for (int ct = 0; ct < NCT; ++ct) S[ct] = (f32x4){0.f, 0.f, 0.f, 0.f};
;     bf16x8 ka[PD][2], vb[PD][NCT][2], qa[PD][4]; f32x4 dc[PD];
;     ...
; #pragma unroll
;     for (int u = 0; u < PD; ++u) P9_LOAD(u, u);
;     for (int c0 = 0; c0 < 128; c0 += PD) {
; #pragma unroll
;         for (int u = 0; u < PD; ++u) {
;             const int c = c0 + u;
;             LAS unsigned char* sl = lds + (u & 1) * P9_SBUF;
; #pragma unroll
;             for (int ct = 0; ct < NCT; ++ct) {
;                 S[ct] = S[ct] * dc[u];
;                 S[ct] = __builtin_amdgcn_mfma_f32_16x16x32_bf16(ka[u][0], vb[u][ct][0], S[ct], 0, 0, 0);
;                 S[ct] = __builtin_amdgcn_mfma_f32_16x16x32_bf16(ka[u][1], vb[u][ct][1], S[ct], 0, 0, 0);
;             }
; #pragma unroll
;             for (int ct = 0; ct < NCT; ++ct) { u32x2 wv; wv.x = cvt_pk_bf16(S[ct][0], S[ct][1]); wv.y = cvt_pk_bf16(S[ct][2], S[ct][3]);
;                 *(LAS u32x2*)(sl + (16 * ct + c16) * 272 + (16 * wave + 4 * kq) * 2) = wv; }
;             asm volatile("s_waitcnt lgkmcnt(0)" ::: "memory"); __builtin_amdgcn_s_barrier(); asm volatile("" ::: "memory");
;             if (RO) {
;                 bf16_t* o2 = op + (size_t)c * 64 * 1024;
; #pragma unroll
;                 for (int ct = 0; ct < NCT; ++ct) {
;                     f32x4 o = (f32x4){0.f, 0.f, 0.f, 0.f};
; #pragma unroll
;                     for (int ks = 0; ks < 4; ++ks) {
;                         const bf16x8 sb = *(const LAS bf16x8*)(sl + (16 * ct + c16) * 272 + (32 * ks + 8 * kq) * 2);
;                         o = __builtin_amdgcn_mfma_f32_16x16x32_bf16(qa[u][ks], sb, o, 0, 0, 0);
;                     }
; #pragma unroll
;                     for (int i = 0; i < 4; ++i) o2[(size_t)i * 1024 + 16 * ct] = (bf16_t)f2bf(o[i]);
;                 }
;             }
;             const int cn = c + PD < 128 ? c + PD : 127;
;             P9_LOAD(u, cn);
;         }
;     }
.LBB0_1042:
	s_ashr_i32 s8, s64, 3
	s_lshr_b32 s39, s8, 28
	s_lshl_b32 s38, s64, 1
	s_add_i32 s39, s8, s39
	s_and_b32 s38, s38, 14
	s_ashr_i32 s65, s39, 4
	s_add_i32 s40, s38, s65
	s_ashr_i32 s41, s40, 31
	s_and_b32 s38, s39, -16
	s_lshl_b64 s[42:43], s[40:41], 21
	s_sub_i32 s66, s8, s38
	s_ashr_i32 s38, s40, 2
	s_and_b32 s8, s40, 3
	v_lshl_add_u64 v[158:159], v[150:151], 0, s[42:43]
	s_lshl_b64 s[42:43], s[40:41], 22
	s_add_u32 s39, s44, s42
	s_addc_u32 s67, s45, s43
	s_lshl_b32 s42, s66, 10
	s_ashr_i32 s43, s42, 31
	s_lshl_b64 s[42:43], s[42:43], 1
	s_add_u32 s42, s39, s42
	s_addc_u32 s43, s67, s43
	v_lshl_add_u64 v[160:161], s[42:43], 0, v[148:149]
	s_lshl_b32 s42, s38, 7
	s_ashr_i32 s43, s42, 31
	s_lshl_b64 s[42:43], s[42:43], 11
	s_add_u32 s39, s46, s42
	s_addc_u32 s42, s47, s43
	s_lshl_b32 s8, s8, 9
	s_add_u32 s8, s39, s8
	s_addc_u32 s39, s42, 0
	s_add_u32 s42, s8, s12
	s_addc_u32 s43, s39, s13
	v_lshl_add_u64 v[162:163], s[42:43], 0, v[156:157]
	s_mov_b64 s[42:43], -1
	s_and_b64 vcc, exec, s[10:11]
	v_lshl_add_u64 v[166:167], v[158:159], 0, s[14:15]
	v_lshl_add_u64 v[124:125], v[158:159], 0, s[16:17]
	v_lshl_add_u64 v[168:169], v[160:161], 0, s[18:19]
	v_lshl_add_u64 v[170:171], v[160:161], 0, s[20:21]
	v_lshl_add_u64 v[172:173], v[162:163], 0, s[22:23]
	s_cbranch_vccz .LBB0_1046
	v_add_co_u32_e32 v0, vcc, 0x4000, v158
	global_load_dwordx4 v[40:43], v[158:159], off
	global_load_dwordx4 v[8:11], v[158:159], off offset:1024
	global_load_dwordx4 v[48:51], v[160:161], off
	global_load_dwordx4 v[16:19], v[160:161], off offset:1024
	v_addc_co_u32_e32 v1, vcc, 0, v159, vcc
	v_add_co_u32_e32 v4, vcc, 0x8000, v160
	global_load_dwordx4 v[24:27], v[0:1], off
	s_nop 0
	global_load_dwordx4 v[0:3], v[0:1], off offset:1024
	v_addc_co_u32_e32 v5, vcc, 0, v161, vcc
	v_add_co_u32_e32 v12, vcc, 0x8000, v158
	global_load_dwordx4 v[36:39], v[4:5], off
	s_nop 0
	global_load_dwordx4 v[4:7], v[4:5], off offset:1024
	s_nop 0
	global_load_dwordx4 v[56:59], v[162:163], off
	global_load_dwordx4 v[44:47], v[162:163], off offset:2048
	v_addc_co_u32_e32 v13, vcc, 0, v159, vcc
	v_add_co_u32_e32 v28, vcc, 0x10000, v160
	global_load_dwordx4 v[20:23], v[12:13], off
	s_nop 0
	global_load_dwordx4 v[12:15], v[12:13], off offset:1024
	v_addc_co_u32_e32 v29, vcc, 0, v161, vcc
	v_add_co_u32_e32 v52, vcc, 0x1000, v162
	global_load_dwordx4 v[32:35], v[28:29], off
	s_nop 0
	global_load_dwordx4 v[28:31], v[28:29], off offset:1024
	v_addc_co_u32_e32 v53, vcc, 0, v163, vcc
	global_load_dwordx4 v[52:55], v[52:53], off
	v_mov_b32_e32 v60, 0
	v_lshl_add_u64 v[64:65], v[158:159], 0, s[14:15]
	v_lshl_add_u64 v[66:67], v[158:159], 0, s[16:17]
	v_lshl_add_u64 v[68:69], v[160:161], 0, s[18:19]
	v_lshl_add_u64 v[70:71], v[160:161], 0, s[20:21]
	v_lshl_add_u64 v[72:73], v[162:163], 0, s[22:23]
	s_mov_b32 s39, -4
	v_mov_b32_e32 v61, v60
	v_mov_b32_e32 v62, v60
	v_mov_b32_e32 v63, v60
	s_waitcnt vmcnt(5)
.LBB0_1044:
	s_waitcnt vmcnt(10)
	v_pk_mul_f32 v[58:59], v[58:59], v[62:63]
	v_pk_mul_f32 v[56:57], v[56:57], v[60:61]
	s_add_i32 s42, s39, 4
	s_add_i32 s8, s39, 5
	v_mfma_f32_16x16x32_bf16 v[40:43], v[40:43], v[48:51], v[56:59]
	s_min_u32 s67, s42, 0x7b
	s_min_u32 s8, s8, 0x7b
	s_add_i32 s67, s67, 4
	v_mfma_f32_16x16x32_bf16 v[8:11], v[8:11], v[16:19], v[40:43]
	s_add_i32 s68, s8, 4
	s_lshl_b32 s8, s67, 14
	v_lshl_add_u64 v[48:49], v[158:159], 0, s[8:9]
	s_lshl_b32 s8, s67, 15
	v_add_u32_e32 v90, v177, v176
	s_nop 2
	v_cvt_pk_bf16_f32 v18, v8, v9
	v_cvt_pk_bf16_f32 v19, v10, v11
	s_waitcnt vmcnt(5)
	v_pk_mul_f32 v[10:11], v[46:47], v[10:11]
	v_pk_mul_f32 v[8:9], v[44:45], v[8:9]
	v_lshl_add_u64 v[16:17], v[160:161], 0, s[8:9]
	s_lshl_b32 s8, s67, 11
	v_mfma_f32_16x16x32_bf16 v[24:27], v[24:27], v[36:39], v[8:11]
	global_load_dwordx4 v[72:75], v[72:73], off
	s_nop 0
	global_load_dwordx4 v[76:79], v[68:69], off
	global_load_dwordx4 v[80:83], v[70:71], off
	s_nop 0
	global_load_dwordx4 v[68:71], v[64:65], off
	global_load_dwordx4 v[84:87], v[66:67], off
	v_lshl_add_u64 v[56:57], v[162:163], 0, s[8:9]
	s_lshl_b32 s8, s68, 14
	v_mfma_f32_16x16x32_bf16 v[0:3], v[0:3], v[4:7], v[24:27]
	ds_write_b64 v90, v[18:19]
	v_lshl_add_u64 v[60:61], v[158:159], 0, s[8:9]
	s_lshl_b32 s8, s68, 15
	s_waitcnt lgkmcnt(0)
	s_barrier
	s_nop 3
	v_cvt_pk_bf16_f32 v4, v0, v1
	v_cvt_pk_bf16_f32 v5, v2, v3
	s_waitcnt vmcnt(5)
	v_pk_mul_f32 v[2:3], v[54:55], v[2:3]
	v_pk_mul_f32 v[0:1], v[52:53], v[0:1]
	v_lshl_add_u64 v[62:63], v[160:161], 0, s[8:9]
	s_lshl_b32 s8, s68, 11
	v_mfma_f32_16x16x32_bf16 v[20:23], v[20:23], v[32:35], v[0:3]
	global_load_dwordx4 v[40:43], v[48:49], off
	global_load_dwordx4 v[8:11], v[48:49], off offset:1024
	s_nop 0
	global_load_dwordx4 v[48:51], v[16:17], off
	s_nop 0
	global_load_dwordx4 v[16:19], v[16:17], off offset:1024
	s_nop 0
	global_load_dwordx4 v[56:59], v[56:57], off
	ds_write_b64 v90, v[4:5] offset:4352
	v_lshl_add_u64 v[44:45], v[162:163], 0, s[8:9]
	s_waitcnt lgkmcnt(0)
	s_barrier
	global_load_dwordx4 v[24:27], v[60:61], off
	global_load_dwordx4 v[0:3], v[60:61], off offset:1024
	global_load_dwordx4 v[36:39], v[62:63], off
	global_load_dwordx4 v[4:7], v[62:63], off offset:1024
	s_nop 0
	global_load_dwordx4 v[44:47], v[44:45], off
	v_mfma_f32_16x16x32_bf16 v[60:63], v[12:15], v[28:31], v[20:23]
	s_add_i32 s43, s39, 6
	s_min_u32 s43, s43, 0x7b
	s_add_i32 s43, s43, 4
	s_lshl_b32 s8, s43, 14
	v_lshl_add_u64 v[64:65], v[158:159], 0, s[8:9]
	s_nop 2
	v_cvt_pk_bf16_f32 v12, v60, v61
	v_cvt_pk_bf16_f32 v13, v62, v63
	s_lshl_b32 s8, s43, 15
	ds_write_b64 v90, v[12:13]
	v_lshl_add_u64 v[66:67], v[160:161], 0, s[8:9]
	s_lshl_b32 s8, s43, 11
	s_waitcnt lgkmcnt(0)
	s_barrier
	v_lshl_add_u64 v[88:89], v[162:163], 0, s[8:9]
	global_load_dwordx4 v[20:23], v[64:65], off
	global_load_dwordx4 v[12:15], v[64:65], off offset:1024
	global_load_dwordx4 v[32:35], v[66:67], off
	global_load_dwordx4 v[28:31], v[66:67], off offset:1024
	global_load_dwordx4 v[52:55], v[88:89], off
	s_add_i32 s8, s39, 7
	s_min_u32 s8, s8, 0x7b
	s_add_i32 s43, s8, 4
	s_lshl_b32 s8, s43, 14
	v_lshl_add_u64 v[64:65], v[158:159], 0, s[8:9]
	s_lshl_b32 s8, s43, 15
	s_mov_b32 s39, s42
	v_lshl_add_u64 v[66:67], v[64:65], 0, s[24:25]
	s_waitcnt vmcnt(19)
	v_pk_mul_f32 v[62:63], v[74:75], v[62:63]
	v_pk_mul_f32 v[60:61], v[72:73], v[60:61]
	s_waitcnt vmcnt(16)
	s_nop 0
	v_mfma_f32_16x16x32_bf16 v[60:63], v[68:71], v[76:79], v[60:63]
	v_lshl_add_u64 v[68:69], v[160:161], 0, s[8:9]
	s_lshl_b32 s8, s43, 11
	s_cmpk_lt_u32 s42, 0x7c
	s_waitcnt vmcnt(15)
	v_mfma_f32_16x16x32_bf16 v[60:63], v[84:87], v[80:83], v[60:63]
	v_lshl_add_u64 v[72:73], v[162:163], 0, s[8:9]
	s_nop 6
	v_cvt_pk_bf16_f32 v70, v60, v61
	v_cvt_pk_bf16_f32 v71, v62, v63
	ds_write_b64 v90, v[70:71] offset:4352
	s_waitcnt lgkmcnt(0)
	s_barrier
	v_lshl_add_u64 v[70:71], v[68:69], 0, s[24:25]
	s_cbranch_scc1 .LBB0_1044
	s_mov_b64 s[42:43], 0
; #define LAS __attribute__((address_space(3)))
; template <bool RO>
; __device__ __forceinline__ void p9_job(LAS unsigned char* lds, const bf16_t* __restrict__ kap, const bf16_t* __restrict__ vbp, const float* __restrict__ dcp, const bf16_t* __restrict__ qap, bf16_t* __restrict__ op, int wave, int c16, int kq) {
;     constexpr int PD = P9_DEPTH, NCT = P9_NCT;
;     f32x4 S[NCT];
; #pragma unroll
;     for (int ct = 0; ct < NCT; ++ct) S[ct] = (f32x4){0.f, 0.f, 0.f, 0.f};
;     bf16x8 ka[PD][2], vb[PD][NCT][2], qa[PD][4]; f32x4 dc[PD];
;     ...
; #pragma unroll
;     for (int u = 0; u < PD; ++u) P9_LOAD(u, u);
;     for (int c0 = 0; c0 < 128; c0 += PD) {
; #pragma unroll
;         for (int u = 0; u < PD; ++u) {
;             const int c = c0 + u;
;             LAS unsigned char* sl = lds + (u & 1) * P9_SBUF;
; #pragma unroll
;             for (int ct = 0; ct < NCT; ++ct) {
;                 S[ct] = S[ct] * dc[u];
;                 S[ct] = __builtin_amdgcn_mfma_f32_16x16x32_bf16(ka[u][0], vb[u][ct][0], S[ct], 0, 0, 0);
;                 S[ct] = __builtin_amdgcn_mfma_f32_16x16x32_bf16(ka[u][1], vb[u][ct][1], S[ct], 0, 0, 0);
;             }
; #pragma unroll
;             for (int ct = 0; ct < NCT; ++ct) { u32x2 wv; wv.x = cvt_pk_bf16(S[ct][0], S[ct][1]); wv.y = cvt_pk_bf16(S[ct][2], S[ct][3]);
;                 *(LAS u32x2*)(sl + (16 * ct + c16) * 272 + (16 * wave + 4 * kq) * 2) = wv; }
;             asm volatile("s_waitcnt lgkmcnt(0)" ::: "memory"); __builtin_amdgcn_s_barrier(); asm volatile("" ::: "memory");
;             if (RO) {
;                 bf16_t* o2 = op + (size_t)c * 64 * 1024;
; #pragma unroll
;                 for (int ct = 0; ct < NCT; ++ct) {
;                     f32x4 o = (f32x4){0.f, 0.f, 0.f, 0.f};
; #pragma unroll
;                     for (int ks = 0; ks < 4; ++ks) {
;                         const bf16x8 sb = *(const LAS bf16x8*)(sl + (16 * ct + c16) * 272 + (32 * ks + 8 * kq) * 2);
;                         o = __builtin_amdgcn_mfma_f32_16x16x32_bf16(qa[u][ks], sb, o, 0, 0, 0);
;                     }
; #pragma unroll
;                     for (int i = 0; i < 4; ++i) o2[(size_t)i * 1024 + 16 * ct] = (bf16_t)f2bf(o[i]);
;                 }
;             }
;             const int cn = c + PD < 128 ? c + PD : 127;
;             P9_LOAD(u, cn);
;         }
;     }
.LBB0_1046:
	s_and_b64 vcc, exec, s[42:43]
	s_cbranch_vccz .LBB0_1041
	s_waitcnt vmcnt(0)
	v_add_co_u32_e32 v24, vcc, s52, v158
	s_lshl_b64 s[40:41], s[40:41], 20
	s_nop 0
	v_addc_co_u32_e32 v25, vcc, 0, v159, vcc
	v_lshl_add_u64 v[164:165], s[40:41], 1, v[152:153]
	global_load_dwordx4 v[40:43], v[158:159], off
	global_load_dwordx4 v[16:19], v[158:159], off offset:1024
	global_load_dwordx4 v[44:47], v[160:161], off
	global_load_dwordx4 v[20:23], v[160:161], off offset:1024
	global_load_dwordx4 v[12:15], v[164:165], off
	global_load_dwordx4 v[8:11], v[164:165], off offset:1024
	global_load_dwordx4 v[0:3], v[164:165], off offset:2048
	global_load_dwordx4 v[4:7], v[164:165], off offset:3072
	global_load_dwordx4 v[68:71], v[24:25], off
	global_load_dwordx4 v[60:63], v[24:25], off offset:1024
	v_add_co_u32_e32 v24, vcc, s53, v160
	s_and_b32 s8, s50, 2
	s_nop 0
	v_addc_co_u32_e32 v25, vcc, 0, v161, vcc
	global_load_dwordx4 v[76:79], v[24:25], off
	global_load_dwordx4 v[72:75], v[24:25], off offset:1024
	global_load_dwordx4 v[140:143], v[162:163], off
	global_load_dwordx4 v[80:83], v[162:163], off offset:2048
	v_add_co_u32_e32 v24, vcc, s52, v164
	s_add_i32 s8, s8, s65
	s_nop 0
	v_addc_co_u32_e32 v25, vcc, 0, v165, vcc
	v_add_co_u32_e32 v48, vcc, s53, v158
	global_load_dwordx4 v[36:39], v[24:25], off
	global_load_dwordx4 v[32:35], v[24:25], off offset:1024
	global_load_dwordx4 v[28:31], v[24:25], off offset:2048
	s_nop 0
	global_load_dwordx4 v[24:27], v[24:25], off offset:3072
	v_addc_co_u32_e32 v49, vcc, 0, v159, vcc
	global_load_dwordx4 v[88:91], v[48:49], off
	global_load_dwordx4 v[84:87], v[48:49], off offset:1024
	v_add_co_u32_e32 v48, vcc, s54, v160
	s_ashr_i32 s39, s38, 31
	s_nop 0
	v_addc_co_u32_e32 v49, vcc, 0, v161, vcc
	global_load_dwordx4 v[96:99], v[48:49], off
	global_load_dwordx4 v[92:95], v[48:49], off offset:1024
	v_add_co_u32_e32 v48, vcc, s55, v162
	s_lshl_b32 s40, s66, 4
	s_nop 0
	v_addc_co_u32_e32 v49, vcc, 0, v163, vcc
	v_add_co_u32_e32 v50, vcc, s53, v164
	s_and_b32 s8, s8, 3
	s_nop 0
	v_addc_co_u32_e32 v51, vcc, 0, v165, vcc
	global_load_dwordx4 v[100:103], v[48:49], off
	global_load_dwordx4 v[64:67], v[50:51], off
	global_load_dwordx4 v[56:59], v[50:51], off offset:1024
	global_load_dwordx4 v[52:55], v[50:51], off offset:2048
	s_nop 0
	global_load_dwordx4 v[48:51], v[50:51], off offset:3072
	s_lshl_b64 s[38:39], s[38:39], 24
	s_ashr_i32 s41, s40, 31
	s_lshl_b32 s8, s8, 9
	s_or_b32 s8, s38, s8
	s_lshl_b64 s[40:41], s[40:41], 1
	s_add_u32 s38, s8, s40
	s_addc_u32 s39, s39, s41
	v_mov_b32_e32 v144, 0
	v_lshl_add_u64 v[116:117], v[164:165], 0, s[14:15]
	v_lshl_add_u64 v[108:109], v[164:165], 0, s[16:17]
	v_lshl_add_u64 v[110:111], v[164:165], 0, s[26:27]
	v_lshl_add_u64 v[120:121], v[164:165], 0, s[28:29]
	v_lshl_add_u64 v[174:175], v[154:155], 0, s[38:39]
	s_mov_b32 s65, -4
	v_mov_b32_e32 v145, v144
	v_mov_b32_e32 v146, v144
	v_mov_b32_e32 v147, v144
	s_waitcnt vmcnt(13)
.LBB0_1048:
	s_waitcnt vmcnt(38)
	v_pk_mul_f32 v[142:143], v[142:143], v[146:147]
	v_pk_mul_f32 v[140:141], v[140:141], v[144:145]
	v_add_u32_e32 v179, v177, v176
	global_load_dwordx4 v[136:139], v[172:173], off
	s_nop 0
	global_load_dwordx4 v[116:119], v[116:117], off
	s_nop 0
	global_load_dwordx4 v[112:115], v[108:109], off
	s_nop 0
	global_load_dwordx4 v[108:111], v[110:111], off
	s_nop 0
	global_load_dwordx4 v[104:107], v[120:121], off
	global_load_dwordx4 v[128:131], v[168:169], off
	s_nop 0
	global_load_dwordx4 v[120:123], v[170:171], off
	global_load_dwordx4 v[132:135], v[166:167], off
	s_nop 0
	global_load_dwordx4 v[124:127], v[124:125], off
	v_mfma_f32_16x16x32_bf16 v[40:43], v[40:43], v[44:47], v[140:143]
	s_add_i32 s66, s65, 4
	s_add_i32 s8, s65, 5
	s_add_i32 s38, s65, 6
	v_mfma_f32_16x16x32_bf16 v[16:19], v[16:19], v[20:23], v[40:43]
	s_min_u32 s40, s66, 0x7b
	v_add_co_u32_e32 v146, vcc, s57, v174
	s_min_u32 s8, s8, 0x7b
	s_min_u32 s38, s38, 0x7b
	s_nop 3
	v_cvt_pk_bf16_f32 v20, v16, v17
	v_cvt_pk_bf16_f32 v21, v18, v19
	ds_write_b64 v179, v[20:21]
	s_waitcnt lgkmcnt(0)
	s_barrier
	ds_read_b128 v[20:23], v178
	s_waitcnt vmcnt(34)
	v_pk_mul_f32 v[18:19], v[82:83], v[18:19]
	v_pk_mul_f32 v[16:17], v[80:81], v[16:17]
	s_waitcnt lgkmcnt(0)
	v_mfma_f32_16x16x32_bf16 v[12:15], v[12:15], v[20:23], 0
	s_add_i32 s40, s40, 4
	v_addc_co_u32_e32 v147, vcc, -1, v175, vcc
	v_mfma_f32_16x16x32_bf16 v[16:19], v[68:71], v[76:79], v[16:19]
	s_mov_b32 s39, s9
	s_mov_b32 s41, s9
	s_add_i32 s67, s8, 4
	v_mfma_f32_16x16x32_bf16 v[60:63], v[60:63], v[72:75], v[16:19]
	ds_read_b128 v[68:71], v178 offset:64
	ds_read_b128 v[72:75], v178 offset:128
	ds_read_b128 v[76:79], v178 offset:192
	s_add_i32 s86, s38, 4
	s_lshl_b32 s8, s40, 14
	s_waitcnt lgkmcnt(2)
	v_mfma_f32_16x16x32_bf16 v[68:71], v[8:11], v[68:71], v[12:15]
	s_waitcnt vmcnt(13)
	v_pk_mul_f32 v[18:19], v[102:103], v[62:63]
	v_pk_mul_f32 v[16:17], v[100:101], v[60:61]
	v_cvt_pk_bf16_f32 v8, v60, v61
	v_cvt_pk_bf16_f32 v9, v62, v63
	s_waitcnt lgkmcnt(1)
	v_mfma_f32_16x16x32_bf16 v[60:63], v[0:3], v[72:75], v[68:71]
	s_lshl_b32 s38, s40, 15
	s_lshl_b32 s40, s40, 11
	v_add_co_u32_e32 v166, vcc, s58, v174
	s_waitcnt lgkmcnt(0)
	v_mfma_f32_16x16x32_bf16 v[60:63], v[4:7], v[76:79], v[60:63]
	v_lshl_add_u64 v[44:45], v[158:159], 0, s[8:9]
	v_lshl_add_u64 v[140:141], v[160:161], 0, s[38:39]
	v_lshl_add_u64 v[142:143], v[162:163], 0, s[40:41]
	v_mfma_f32_16x16x32_bf16 v[80:83], v[88:91], v[96:99], v[16:19]
	v_lshl_add_u64 v[172:173], v[164:165], 0, s[8:9]
	s_nop 2
	v_bfe_u32 v68, v60, 16, 1
	v_bfe_u32 v69, v61, 16, 1
	v_bfe_u32 v70, v62, 16, 1
	v_bfe_u32 v71, v63, 16, 1
	v_add3_u32 v60, v60, v68, s56
	v_addc_co_u32_e32 v167, vcc, -1, v175, vcc
	global_load_dwordx4 v[40:43], v[44:45], off
	global_load_dwordx4 v[16:19], v[44:45], off offset:1024
	s_nop 0
	global_load_dwordx4 v[44:47], v[140:141], off
	global_load_dwordx4 v[20:23], v[140:141], off offset:1024
	s_nop 0
	global_load_dwordx4 v[140:143], v[142:143], off
	s_nop 0
	global_load_dwordx4 v[12:15], v[172:173], off
	ds_write_b64 v179, v[8:9] offset:4352
	global_load_dwordx4 v[8:11], v[172:173], off offset:1024
	global_load_dwordx4 v[0:3], v[172:173], off offset:2048
	global_load_dwordx4 v[4:7], v[172:173], off offset:3072
	v_add3_u32 v61, v61, v69, s56
	v_add3_u32 v62, v62, v70, s56
	v_add3_u32 v63, v63, v71, s56
	global_store_short_d16_hi v[146:147], v60, off offset:-2048
	global_store_short_d16_hi v[166:167], v61, off offset:-4096
	global_store_short_d16_hi v[166:167], v62, off offset:-2048
	global_store_short_d16_hi v[166:167], v63, off
	s_waitcnt lgkmcnt(0)
	s_barrier
; #define LAS __attribute__((address_space(3)))
; __device__ __forceinline__ unsigned cvt_pk_bf16(float lo, float hi) { f32x2_t v = {lo, hi}; bf16x2_t b = __builtin_convertvector(v, bf16x2_t); return __builtin_bit_cast(unsigned, b); }
; __device__ __forceinline__ unsigned f2bf(float f) { unsigned u = __builtin_bit_cast(unsigned, f); return (u + 0x7fffu + ((u >> 16) & 1u)) >> 16; }
; template <bool RO>
; __device__ __forceinline__ void p9_job(LAS unsigned char* lds, const bf16_t* __restrict__ kap, const bf16_t* __restrict__ vbp, const float* __restrict__ dcp, const bf16_t* __restrict__ qap, bf16_t* __restrict__ op, int wave, int c16, int kq) {
;     ...
;     for (int c0 = 0; c0 < 128; c0 += PD) {
; #pragma unroll
;         for (int u = 0; u < PD; ++u) {
;             const int c = c0 + u;
;             LAS unsigned char* sl = lds + (u & 1) * P9_SBUF;
; #pragma unroll
;             for (int ct = 0; ct < NCT; ++ct) {
;                 S[ct] = S[ct] * dc[u];
;                 S[ct] = __builtin_amdgcn_mfma_f32_16x16x32_bf16(ka[u][0], vb[u][ct][0], S[ct], 0, 0, 0);
;                 S[ct] = __builtin_amdgcn_mfma_f32_16x16x32_bf16(ka[u][1], vb[u][ct][1], S[ct], 0, 0, 0);
;             }
; #pragma unroll
;             for (int ct = 0; ct < NCT; ++ct) { u32x2 wv; wv.x = cvt_pk_bf16(S[ct][0], S[ct][1]); wv.y = cvt_pk_bf16(S[ct][2], S[ct][3]);
;                 *(LAS u32x2*)(sl + (16 * ct + c16) * 272 + (16 * wave + 4 * kq) * 2) = wv; }
;             asm volatile("s_waitcnt lgkmcnt(0)" ::: "memory"); __builtin_amdgcn_s_barrier(); asm volatile("" ::: "memory");
;             if (RO) {
;                 bf16_t* o2 = op + (size_t)c * 64 * 1024;
; #pragma unroll
;                 for (int ct = 0; ct < NCT; ++ct) {
;                     f32x4 o = (f32x4){0.f, 0.f, 0.f, 0.f};
; #pragma unroll
;                     for (int ks = 0; ks < 4; ++ks) {
;                         const bf16x8 sb = *(const LAS bf16x8*)(sl + (16 * ct + c16) * 272 + (32 * ks + 8 * kq) * 2);
;                         o = __builtin_amdgcn_mfma_f32_16x16x32_bf16(qa[u][ks], sb, o, 0, 0, 0);
;                     }
; #pragma unroll
;                     for (int i = 0; i < 4; ++i) o2[(size_t)i * 1024 + 16 * ct] = (bf16_t)f2bf(o[i]);
;                 }
;             }
;             const int cn = c + PD < 128 ? c + PD : 127;
;             P9_LOAD(u, cn);
;         }
;     }
	v_mfma_f32_16x16x32_bf16 v[180:183], v[84:87], v[92:95], v[80:83]
	ds_read_b128 v[60:63], v178 offset:4352
	ds_read_b128 v[72:75], v178 offset:4416
	ds_read_b128 v[84:87], v178 offset:4480
	ds_read_b128 v[88:91], v178 offset:4544
	v_add_co_u32_e32 v168, vcc, s59, v174
	s_waitcnt lgkmcnt(3)
	v_mfma_f32_16x16x32_bf16 v[36:39], v[36:39], v[60:63], 0
	s_mov_b32 s43, s9
	s_lshl_b32 s42, s67, 15
	s_lshl_b32 s8, s67, 14
	s_waitcnt lgkmcnt(2)
	v_mfma_f32_16x16x32_bf16 v[32:35], v[32:35], v[72:75], v[36:39]
	v_addc_co_u32_e32 v169, vcc, -1, v175, vcc
	s_mov_b32 s69, s9
	s_waitcnt lgkmcnt(1)
	v_mfma_f32_16x16x32_bf16 v[84:87], v[28:31], v[84:87], v[32:35]
	s_lshl_b32 s68, s67, 11
	v_lshl_add_u64 v[184:185], v[160:161], 0, s[42:43]
	v_lshl_add_u64 v[194:195], v[158:159], 0, s[8:9]
	s_waitcnt lgkmcnt(0)
	v_mfma_f32_16x16x32_bf16 v[84:87], v[24:27], v[88:91], v[84:87]
	v_cvt_pk_bf16_f32 v92, v180, v181
	v_cvt_pk_bf16_f32 v93, v182, v183
	v_add_co_u32_e32 v170, vcc, s60, v174
	v_lshl_add_u64 v[186:187], v[162:163], 0, s[68:69]
	s_nop 3
	v_bfe_u32 v88, v84, 16, 1
	v_lshl_add_u64 v[196:197], v[164:165], 0, s[8:9]
	global_load_dwordx4 v[68:71], v[194:195], off
	global_load_dwordx4 v[60:63], v[194:195], off offset:1024
	global_load_dwordx4 v[76:79], v[184:185], off
	global_load_dwordx4 v[72:75], v[184:185], off offset:1024
	global_load_dwordx4 v[80:83], v[186:187], off
	ds_write_b64 v179, v[92:93]
	v_bfe_u32 v89, v85, 16, 1
	v_bfe_u32 v90, v86, 16, 1
	v_bfe_u32 v91, v87, 16, 1
	v_add3_u32 v84, v84, v88, s56
	v_addc_co_u32_e32 v171, vcc, -1, v175, vcc
	global_load_dwordx4 v[36:39], v[196:197], off
	global_load_dwordx4 v[32:35], v[196:197], off offset:1024
	global_load_dwordx4 v[28:31], v[196:197], off offset:2048
	global_load_dwordx4 v[24:27], v[196:197], off offset:3072
	v_add3_u32 v85, v85, v89, s56
	v_add3_u32 v86, v86, v90, s56
	v_add3_u32 v87, v87, v91, s56
	global_store_short_d16_hi v[168:169], v84, off offset:-2048
	global_store_short_d16_hi v[170:171], v85, off offset:-4096
	global_store_short_d16_hi v[170:171], v86, off offset:-2048
	global_store_short_d16_hi v[170:171], v87, off
	s_waitcnt lgkmcnt(0)
	s_barrier
	ds_read_b128 v[84:87], v178
	ds_read_b128 v[92:95], v178 offset:64
	ds_read_b128 v[166:169], v178 offset:128
	s_waitcnt vmcnt(38) lgkmcnt(2)
	v_mfma_f32_16x16x32_bf16 v[64:67], v[64:67], v[84:87], 0
	ds_read_b128 v[170:173], v178 offset:192
	s_mov_b32 s71, s9
	s_lshl_b32 s70, s86, 15
	s_waitcnt vmcnt(37) lgkmcnt(2)
	v_mfma_f32_16x16x32_bf16 v[56:59], v[56:59], v[92:95], v[64:67]
	s_lshl_b32 s8, s86, 14
	s_mov_b32 s77, s9
	s_lshl_b32 s76, s86, 11
	s_waitcnt vmcnt(36) lgkmcnt(1)
	v_mfma_f32_16x16x32_bf16 v[166:169], v[52:55], v[166:169], v[56:59]
	v_lshl_add_u64 v[190:191], v[160:161], 0, s[70:71]
	v_lshl_add_u64 v[198:199], v[158:159], 0, s[8:9]
	v_lshl_add_u64 v[200:201], v[164:165], 0, s[8:9]
	v_lshl_add_u64 v[192:193], v[162:163], 0, s[76:77]
	global_load_dwordx4 v[88:91], v[198:199], off
	global_load_dwordx4 v[84:87], v[198:199], off offset:1024
	global_load_dwordx4 v[96:99], v[190:191], off
	global_load_dwordx4 v[92:95], v[190:191], off offset:1024
	global_load_dwordx4 v[100:103], v[192:193], off
	global_load_dwordx4 v[64:67], v[200:201], off
	global_load_dwordx4 v[56:59], v[200:201], off offset:1024
	global_load_dwordx4 v[52:55], v[200:201], off offset:2048
	s_waitcnt vmcnt(43) lgkmcnt(0)
	v_mfma_f32_16x16x32_bf16 v[184:187], v[48:51], v[170:173], v[166:169]
	global_load_dwordx4 v[48:51], v[200:201], off offset:3072
	s_waitcnt vmcnt(43)
	v_pk_mul_f32 v[138:139], v[138:139], v[182:183]
	v_pk_mul_f32 v[136:137], v[136:137], v[180:181]
	v_add_co_u32_e32 v144, vcc, s61, v174
	s_waitcnt vmcnt(36)
	v_mfma_f32_16x16x32_bf16 v[128:131], v[132:135], v[128:131], v[136:139]
	v_addc_co_u32_e32 v145, vcc, -1, v175, vcc
	v_bfe_u32 v146, v184, 16, 1
	v_bfe_u32 v147, v185, 16, 1
	v_add_co_u32_e32 v188, vcc, s62, v174
	v_bfe_u32 v180, v186, 16, 1
	v_bfe_u32 v181, v187, 16, 1
	v_add3_u32 v146, v184, v146, s56
	v_add3_u32 v147, v185, v147, s56
	v_addc_co_u32_e32 v189, vcc, -1, v175, vcc
	v_add3_u32 v180, v186, v180, s56
	v_add3_u32 v181, v187, v181, s56
	global_store_short_d16_hi v[144:145], v146, off offset:-2048
	global_store_short_d16_hi v[188:189], v147, off offset:-4096
	global_store_short_d16_hi v[188:189], v180, off offset:-2048
	global_store_short_d16_hi v[188:189], v181, off
	s_waitcnt vmcnt(39)
	v_mfma_f32_16x16x32_bf16 v[144:147], v[124:127], v[120:123], v[128:131]
	s_add_i32 s8, s65, 7
	s_min_u32 s8, s8, 0x7b
	s_add_i32 s8, s8, 4
	v_add_co_u32_e32 v190, vcc, s63, v174
	s_lshl_b32 s38, s8, 15
	s_nop 2
	v_cvt_pk_bf16_f32 v120, v144, v145
	v_cvt_pk_bf16_f32 v121, v146, v147
	ds_write_b64 v179, v[120:121] offset:4352
	s_waitcnt lgkmcnt(0)
	s_barrier
	ds_read_b128 v[120:123], v178 offset:4352
	ds_read_b128 v[126:129], v178 offset:4416
	s_waitcnt lgkmcnt(1)
	v_mfma_f32_16x16x32_bf16 v[118:121], v[116:119], v[120:123], 0
	s_lshl_b32 s40, s8, 11
	s_lshl_b32 s8, s8, 14
	v_addc_co_u32_e32 v191, vcc, -1, v175, vcc
	s_waitcnt lgkmcnt(0)
	v_mfma_f32_16x16x32_bf16 v[112:115], v[112:115], v[126:129], v[118:121]
	s_nop 2
	ds_read_b128 v[118:121], v178 offset:4480
	ds_read_b128 v[126:129], v178 offset:4544
	v_lshl_add_u64 v[168:169], v[160:161], 0, s[38:39]
	v_lshl_add_u64 v[166:167], v[158:159], 0, s[8:9]
	s_waitcnt lgkmcnt(1)
	v_mfma_f32_16x16x32_bf16 v[112:115], v[108:111], v[118:121], v[112:115]
	v_lshl_add_u64 v[116:117], v[164:165], 0, s[8:9]
	s_mov_b32 s65, s66
	v_lshl_add_u64 v[172:173], v[162:163], 0, s[40:41]
	s_waitcnt lgkmcnt(0)
	v_mfma_f32_16x16x32_bf16 v[104:107], v[104:107], v[126:129], v[112:115]
	v_lshl_add_u64 v[170:171], v[168:169], 0, s[24:25]
	s_cmpk_gt_u32 s66, 0x7b
	v_lshl_add_u64 v[124:125], v[166:167], 0, s[24:25]
	v_lshl_add_u64 v[108:109], v[116:117], 0, s[24:25]
	v_lshl_add_u64 v[110:111], v[116:117], 0, s[30:31]
	s_nop 2
	v_bfe_u32 v112, v104, 16, 1
	v_bfe_u32 v113, v105, 16, 1
	v_bfe_u32 v114, v106, 16, 1
	v_bfe_u32 v115, v107, 16, 1
	v_add3_u32 v104, v104, v112, s56
	v_lshl_add_u64 v[120:121], v[116:117], 0, s[34:35]
	v_add3_u32 v105, v105, v113, s56
	v_add3_u32 v106, v106, v114, s56
	v_add3_u32 v107, v107, v115, s56
	global_store_short_d16_hi v[190:191], v104, off offset:-2048
	global_store_short_d16_hi v[174:175], v105, off offset:-4096
	global_store_short_d16_hi v[174:175], v106, off offset:-2048
	global_store_short_d16_hi v[174:175], v107, off
	v_lshl_add_u64 v[174:175], v[174:175], 0, s[36:37]
	s_cbranch_scc0 .LBB0_1048
	s_branch .LBB0_1041
